# attention loop: dropped four NaN-canonicalising max ops from the row-max chain
# speedup vs baseline: 1.0282x; 1.0031x over previous
; #define LAS __attribute__((address_space(3)))
; __device__ __forceinline__ float xor32_max(float v) { const auto rr = __builtin_amdgcn_permlane32_swap(__float_as_uint(v), __float_as_uint(v), false, false); return fmaxf(__uint_as_float(rr[0]), __uint_as_float(rr[1])); }
; template <bool NA> ...
;     ...
;             const LAS unsigned char* kb = lds + cur * KB; const LAS unsigned char* vb = lds + VOFF + cur * VB;
;             f32x16 p0, p1;
;             if (NA) {
; #pragma unroll
;                 for (int r = 0; r < 16; ++r) { p0[r] = 0.f; p1[r] = 0.f; }
;             } else { p0 = negm; p1 = negm; }
;             bf16x8 kf[8], vfr[8];
; #pragma unroll
;             for (int s = 0; s < 4; ++s) {
;                 kf[2 * s] = *(const LAS bf16x8*)(kb + q * 144 + (16 * s + 8 * h) * 2);
;                 kf[2 * s + 1] = *(const LAS bf16x8*)(kb + (q + 32) * 144 + (16 * s + 8 * h) * 2);
;             }
; #pragma unroll
;             for (int s = 0; s < 4; ++s) {
;                 vfr[2 * s] = *(const LAS bf16x8*)(vb + q * 144 + 32 * s + 16 * h);
;                 vfr[2 * s + 1] = *(const LAS bf16x8*)(vb + (q + 32) * 144 + 32 * s + 16 * h);
;             }
;             __builtin_amdgcn_sched_barrier(0);
;             __builtin_amdgcn_s_setprio(1);
; #pragma unroll
;             for (int s = 0; s < 4; ++s) {
;                 p0 = __builtin_amdgcn_mfma_f32_32x32x16_bf16(kf[2 * s], qb[s], p0, 0, 0, 0);
;                 p1 = __builtin_amdgcn_mfma_f32_32x32x16_bf16(kf[2 * s + 1], qb[s], p1, 0, 0, 0);
;             }
;     ...
;             float mx = fmaxf(fmaxf(p0[0], p1[0]), p0[1]), mx2 = fmaxf(fmaxf(p1[1], p0[2]), p1[2]);
; #pragma unroll
;             for (int r = 3; r < 15; r += 3) { mx = fmaxf(fmaxf(mx, p0[r]), p1[r]); mx2 = fmaxf(fmaxf(mx2, p0[r + 1]), p1[r + 1]); mx = fmaxf(fmaxf(mx, p0[r + 2]), p1[r + 2]); }
;             mx = fmaxf(fmaxf(mx, mx2), fmaxf(p0[15], p1[15]));
;             mx = xor32_max(mx);
;             const bool need = (mx > 0.f) || (j == 0);
;             if (__builtin_amdgcn_ballot_w64(need) != 0ull) {
;                 const float delta = need ? mx : 0.f;
;                 const float alpha = __builtin_amdgcn_exp2f(-delta);
;                 m += delta; l *= alpha;
; #pragma unroll
;                 for (int r = 0; r < 16; ++r) { o0[r] *= alpha; o1[r] *= alpha; p0[r] -= delta; p1[r] -= delta; negm[r] = -m; }
.LBB0_307:
	s_and_b32 s20, s2, 1
	s_mul_i32 s22, s20, 0x2400
	v_add_u32_e32 v50, s22, v194
	ds_read_b128 v[66:69], v50
	ds_read_b128 v[144:147], v50 offset:32
	ds_read_b128 v[148:151], v50 offset:4608
	ds_read_b128 v[188:191], v50 offset:4640
	ds_read_b128 v[196:199], v50 offset:64
	ds_read_b128 v[218:221], v50 offset:96
	ds_read_b128 v[222:225], v50 offset:4672
	ds_read_b128 v[226:229], v50 offset:4704
	ds_read_b128 v[134:137], v50 offset:18432
	ds_read_b128 v[126:129], v50 offset:18464
	ds_read_b128 v[130:133], v50 offset:23040
	ds_read_b128 v[122:125], v50 offset:23072
	ds_read_b128 v[118:121], v50 offset:18496
	ds_read_b128 v[90:93], v50 offset:18528
	ds_read_b128 v[114:117], v50 offset:23104
	ds_read_b128 v[94:97], v50 offset:23136
	s_setprio 1
	s_waitcnt lgkmcnt(14)
	v_mfma_f32_32x32x16_bf16 v[50:65], v[66:69], v[98:101], v[2:17]
	v_mfma_f32_32x32x16_bf16 v[50:65], v[144:147], v[102:105], v[50:65]
	s_waitcnt lgkmcnt(13)
	v_mfma_f32_32x32x16_bf16 v[66:81], v[148:151], v[98:101], v[2:17]
	s_waitcnt lgkmcnt(12)
	v_mfma_f32_32x32x16_bf16 v[66:81], v[188:191], v[102:105], v[66:81]
	s_waitcnt lgkmcnt(11)
	v_mfma_f32_32x32x16_bf16 v[50:65], v[196:199], v[106:109], v[50:65]
	s_waitcnt lgkmcnt(9)
	v_mfma_f32_32x32x16_bf16 v[66:81], v[222:225], v[106:109], v[66:81]
	v_mfma_f32_32x32x16_bf16 v[50:65], v[218:221], v[110:113], v[50:65]
	s_waitcnt lgkmcnt(8)
	v_mfma_f32_32x32x16_bf16 v[66:81], v[226:229], v[110:113], v[66:81]
	s_setprio 0
	s_nop 10
	v_max3_f32 v143, v50, v66, v51
	v_max3_f32 v143, v143, v53, v69
	v_max3_f32 v143, v143, v55, v71
	v_max3_f32 v143, v143, v56, v72
	v_max3_f32 v144, v67, v52, v68
	v_max3_f32 v143, v143, v58, v74
	v_max3_f32 v144, v144, v54, v70
	v_max3_f32 v143, v143, v59, v75
	v_max3_f32 v144, v144, v57, v73
	v_max3_f32 v143, v143, v61, v77
	v_max3_f32 v144, v144, v60, v76
	v_max3_f32 v143, v143, v62, v78
	v_max3_f32 v144, v144, v63, v79
	v_max3_f32 v143, v143, v64, v80
	v_max_f32_e32 v145, v65, v81
	v_max3_f32 v143, v143, v144, v145
	v_mov_b32_e32 v144, v143
	s_nop 1
	v_permlane32_swap_b32_e32 v143, v144
	v_max_f32_e32 v143, v143, v144
	v_cmp_lt_f32_e32 vcc, 0, v143
	s_cbranch_vccz .LBB0_309
	s_nop 0
	v_cndmask_b32_e32 v4, 0, v143, vcc
	v_exp_f32_e64 v6, -v4
	v_add_f32_e32 v183, v183, v4
	v_xor_b32_e32 v2, 0x80000000, v183
	v_pk_add_f32 v[50:51], v[50:51], v[4:5] op_sel_hi:[1,0] neg_lo:[0,1] neg_hi:[0,1]
	v_pk_add_f32 v[66:67], v[66:67], v[4:5] op_sel_hi:[1,0] neg_lo:[0,1] neg_hi:[0,1]
	v_pk_add_f32 v[52:53], v[52:53], v[4:5] op_sel_hi:[1,0] neg_lo:[0,1] neg_hi:[0,1]
	v_pk_add_f32 v[68:69], v[68:69], v[4:5] op_sel_hi:[1,0] neg_lo:[0,1] neg_hi:[0,1]
	v_pk_add_f32 v[54:55], v[54:55], v[4:5] op_sel_hi:[1,0] neg_lo:[0,1] neg_hi:[0,1]
	v_pk_add_f32 v[70:71], v[70:71], v[4:5] op_sel_hi:[1,0] neg_lo:[0,1] neg_hi:[0,1]
	v_pk_add_f32 v[56:57], v[56:57], v[4:5] op_sel_hi:[1,0] neg_lo:[0,1] neg_hi:[0,1]
	v_pk_add_f32 v[72:73], v[72:73], v[4:5] op_sel_hi:[1,0] neg_lo:[0,1] neg_hi:[0,1]
	v_pk_add_f32 v[58:59], v[58:59], v[4:5] op_sel_hi:[1,0] neg_lo:[0,1] neg_hi:[0,1]
	v_pk_add_f32 v[74:75], v[74:75], v[4:5] op_sel_hi:[1,0] neg_lo:[0,1] neg_hi:[0,1]
	v_pk_add_f32 v[60:61], v[60:61], v[4:5] op_sel_hi:[1,0] neg_lo:[0,1] neg_hi:[0,1]
	v_pk_add_f32 v[76:77], v[76:77], v[4:5] op_sel_hi:[1,0] neg_lo:[0,1] neg_hi:[0,1]
	v_pk_add_f32 v[62:63], v[62:63], v[4:5] op_sel_hi:[1,0] neg_lo:[0,1] neg_hi:[0,1]
	v_pk_add_f32 v[78:79], v[78:79], v[4:5] op_sel_hi:[1,0] neg_lo:[0,1] neg_hi:[0,1]
	v_pk_mul_f32 v[48:49], v[48:49], v[6:7] op_sel_hi:[1,0]
	v_pk_mul_f32 v[46:47], v[46:47], v[6:7] op_sel_hi:[1,0]
	v_pk_mul_f32 v[44:45], v[44:45], v[6:7] op_sel_hi:[1,0]
	v_pk_mul_f32 v[42:43], v[42:43], v[6:7] op_sel_hi:[1,0]
	v_pk_mul_f32 v[40:41], v[40:41], v[6:7] op_sel_hi:[1,0]
	v_pk_mul_f32 v[38:39], v[38:39], v[6:7] op_sel_hi:[1,0]
	v_pk_mul_f32 v[36:37], v[36:37], v[6:7] op_sel_hi:[1,0]
	v_pk_mul_f32 v[34:35], v[34:35], v[6:7] op_sel_hi:[1,0]
	v_pk_mul_f32 v[32:33], v[32:33], v[6:7] op_sel_hi:[1,0]
	v_pk_mul_f32 v[30:31], v[30:31], v[6:7] op_sel_hi:[1,0]
	v_pk_mul_f32 v[28:29], v[28:29], v[6:7] op_sel_hi:[1,0]
	v_pk_mul_f32 v[26:27], v[26:27], v[6:7] op_sel_hi:[1,0]
	v_pk_mul_f32 v[24:25], v[24:25], v[6:7] op_sel_hi:[1,0]
	v_pk_mul_f32 v[22:23], v[22:23], v[6:7] op_sel_hi:[1,0]
	v_pk_mul_f32 v[20:21], v[20:21], v[6:7] op_sel_hi:[1,0]
	v_pk_mul_f32 v[18:19], v[18:19], v[6:7] op_sel_hi:[1,0]
	v_pk_add_f32 v[64:65], v[64:65], v[4:5] op_sel_hi:[1,0] neg_lo:[0,1] neg_hi:[0,1]
	v_pk_add_f32 v[80:81], v[80:81], v[4:5] op_sel_hi:[1,0] neg_lo:[0,1] neg_hi:[0,1]
	v_mul_f32_e32 v142, v142, v6
	v_mov_b32_e32 v3, v2
	v_mov_b32_e32 v4, v2
	v_mov_b32_e32 v5, v2
	v_mov_b32_e32 v6, v2
	v_mov_b32_e32 v7, v2
	v_mov_b32_e32 v8, v2
	v_mov_b32_e32 v9, v2
	v_mov_b32_e32 v10, v2
	v_mov_b32_e32 v11, v2
	v_mov_b32_e32 v12, v2
	v_mov_b32_e32 v13, v2
	v_mov_b32_e32 v14, v2
	v_mov_b32_e32 v15, v2
	v_mov_b32_e32 v16, v2
	v_mov_b32_e32 v17, v2
